# split phase-0 weight transposes spread as 2 tiles on all 512 workgroups (modulation workgroups included) instead of 3 tiles on workgroups 0..319
# speedup vs baseline: 1.0011x; 1.0011x over previous
.LBB0_33:
	s_load_dwordx2 s[24:25], s[0:1], 0x38
	s_load_dwordx2 s[26:27], s[0:1], 0x78
	s_waitcnt lgkmcnt(0)
	s_mov_b32 s23, s96
	s_movk_i32 s4, 0x2c0
	s_cmpk_lt_u32 s23, 0x2c0
	s_cselect_b32 s4, 0x0, s4
	s_add_i32 s23, s23, s4
	s_cmpk_gt_i32 s23, 0x57f
	s_cbranch_scc1 .Lpb_out0
	s_mul_hi_i32 s4, s23, 0x2e8ba2e9
	s_ashr_i32 s4, s4, 7
	s_mul_i32 s6, s4, 0x2c0
	s_sub_i32 s6, s23, s6
	s_mul_i32 s7, s6, 0xba3
	s_lshr_b32 s7, s7, 17
	s_mul_i32 s8, s7, 44
	s_sub_i32 s6, s6, s8
	s_mul_i32 s8, s4, 0xb00000
	s_mul_i32 s9, s7, 0xb0000
	s_add_u32 s8, s8, s9
	s_lshl_b32 s9, s6, 8
	s_add_u32 s8, s8, s9
	s_add_u32 s36, s24, s8
	s_addc_u32 s37, s25, 0
	s_sub_i32 s9, s6, 20
	s_cmp_gt_u32 s9, 15
	s_cbranch_scc1 .Lpb_nr0
	s_and_b32 s16, s6, 3
	s_lshr_b32 s9, s9, 2
	s_lshl_b32 s9, s9, 3
	s_lshr_b32 s9, 0x1d15141c, s9
	s_and_b32 s9, s9, 0xff
	s_lshl_b32 s16, s16, 1
	s_add_i32 s6, s9, s16

.Lpb_dec0:
	v_mad_u32_u24 v72, v22, s40, v0
	s_lshl_b32 s17, s40, 4
	global_load_dwordx4 v[208:211], v72, s[36:37] nt
	s_add_u32 s36, s36, s17
	s_addc_u32 s37, s37, 0
	global_load_dwordx4 v[212:215], v72, s[36:37] nt
	s_add_u32 s36, s36, s17
	s_addc_u32 s37, s37, 0
	global_load_dwordx4 v[216:219], v72, s[36:37] nt
	s_add_u32 s36, s36, s17
	s_addc_u32 s37, s37, 0
	global_load_dwordx4 v[220:223], v72, s[36:37] nt
	s_add_i32 s23, s96, 0x200
	s_cmpk_gt_u32 s23, 0x3bf
	s_cbranch_scc1 .Lpb_dummy
	s_movk_i32 s4, 0x2c0
	s_cmpk_lt_u32 s23, 0x2c0
	s_cselect_b32 s4, 0x0, s4
	s_add_i32 s23, s23, s4
	s_cmpk_gt_i32 s23, 0x57f
	s_cbranch_scc1 .Lpb_out1
	s_mul_hi_i32 s4, s23, 0x2e8ba2e9
	s_ashr_i32 s4, s4, 7
	s_mul_i32 s6, s4, 0x2c0
	s_sub_i32 s6, s23, s6
	s_mul_i32 s7, s6, 0xba3
	s_lshr_b32 s7, s7, 17
	s_mul_i32 s8, s7, 44
	s_sub_i32 s6, s6, s8
	s_mul_i32 s8, s4, 0xb00000
	s_mul_i32 s9, s7, 0xb0000
	s_add_u32 s8, s8, s9
	s_lshl_b32 s9, s6, 8
	s_add_u32 s8, s8, s9
	s_add_u32 s42, s24, s8
	s_addc_u32 s43, s25, 0
	s_sub_i32 s9, s6, 20
	s_cmp_gt_u32 s9, 15
	s_cbranch_scc1 .Lpb_nr1
	s_and_b32 s16, s6, 3
	s_lshr_b32 s9, s9, 2
	s_lshl_b32 s9, s9, 3
	s_lshr_b32 s9, 0x1d15141c, s9
	s_and_b32 s9, s9, 0xff
	s_lshl_b32 s16, s16, 1
	s_add_i32 s6, s9, s16

.Lpb_dec1:
	s_mov_b32 s4, 1
.Lpb_ldl:
	v_mad_u32_u24 v73, v22, s41, v0
	s_lshl_b32 s17, s41, 4
	global_load_dwordx4 v[224:227], v73, s[42:43] nt
	s_add_u32 s42, s42, s17
	s_addc_u32 s43, s43, 0
	global_load_dwordx4 v[228:231], v73, s[42:43] nt
	s_add_u32 s42, s42, s17
	s_addc_u32 s43, s43, 0
	global_load_dwordx4 v[232:235], v73, s[42:43] nt
	s_add_u32 s42, s42, s17
	s_addc_u32 s43, s43, 0
	global_load_dwordx4 v[236:239], v73, s[42:43] nt
.Lpb_done:
	s_movk_i32 s23, 0x780
	s_load_dwordx16 s[36:51], s[0:1], 0x0

.LBB0_120:
	s_or_b64 exec, exec, s[8:9]
	s_load_dwordx2 s[24:25], s[0:1], 0x38
	s_load_dwordx2 s[26:27], s[0:1], 0x78
	s_add_u32 s28, s94, 0xd00000
	s_addc_u32 s29, s95, 0
	s_add_u32 s30, s94, 0x200000
	s_addc_u32 s31, s95, 0
	v_lshrrev_b32_e32 v22, 4, v138
	v_and_b32_e32 v0, 15, v138
	v_lshlrev_b32_e32 v0, 4, v0
	v_and_b32_e32 v2, 3, v138
	v_lshlrev_b32_e32 v24, 4, v2
	v_lshlrev_b32_e32 v2, 5, v2
	v_lshrrev_b32_e32 v23, 2, v138
	v_mul_u32_u24_e32 v24, 0x41, v24
	v_and_b32_e32 v25, -4, v138
	v_lshl_add_u32 v24, v24, 2, v25
	v_mul_u32_u24_e32 v25, 0x104, v22
	v_add_u32_e32 v25, v25, v0
	v_add_u32_e32 v26, 0x1040, v25
	v_add_u32_e32 v27, 0x1048, v25
	v_add_u32_e32 v28, 0x2080, v25
	v_add_u32_e32 v29, 0x2088, v25
	v_add_u32_e32 v30, 0x30c0, v25
	v_add_u32_e32 v31, 0x30c8, v25
	v_add_u32_e32 v83, 0x400, v24
	v_add_u32_e32 v84, 0x800, v24
	v_add_u32_e32 v85, 0xc00, v24
	s_waitcnt lgkmcnt(0)
	v_lshl_add_u32 v82, v23, 11, v2
	s_mov_b32 s4, s96
	s_movk_i32 s86, 0x2c0
	s_cmpk_lt_u32 s4, 0x2c0
	s_cselect_b32 s86, 0x0, s86
	s_add_i32 s4, s4, s86
	s_cmpk_gt_i32 s4, 0x57f
	s_cbranch_scc1 .Lpc_out0
	s_mul_hi_i32 s86, s4, 0x2e8ba2e9
	s_ashr_i32 s86, s86, 7
	s_mul_i32 s87, s86, 0x2c0
	s_sub_i32 s87, s4, s87
	s_mul_i32 s88, s87, 0xba3
	s_lshr_b32 s88, s88, 17
	s_mul_i32 s89, s88, 44
	s_sub_i32 s87, s87, s89
	s_mul_i32 s89, s86, 0xb00000
	s_mul_i32 s90, s88, 0xb0000
	s_add_u32 s89, s89, s90
	s_lshl_b32 s90, s87, 8
	s_add_u32 s89, s89, s90
	s_add_u32 s76, s24, s89
	s_addc_u32 s77, s25, 0
	s_sub_i32 s90, s87, 20
	s_cmp_gt_u32 s90, 15
	s_cbranch_scc1 .Lpc_nr0
	s_and_b32 s91, s87, 3
	s_lshr_b32 s90, s90, 2
	s_lshl_b32 s90, s90, 3
	s_lshr_b32 s90, 0x1d15141c, s90
	s_and_b32 s90, s90, 0xff
	s_lshl_b32 s91, s91, 1
	s_add_i32 s87, s90, s91

.Lpc_dec0:
	s_add_i32 s4, s96, 0x200
	s_cmpk_gt_u32 s4, 0x3bf
	s_cbranch_scc1 .Lpc_dummy
	s_movk_i32 s86, 0x2c0
	s_cmpk_lt_u32 s4, 0x2c0
	s_cselect_b32 s86, 0x0, s86
	s_add_i32 s4, s4, s86
	s_cmpk_gt_i32 s4, 0x57f
	s_cbranch_scc1 .Lpc_out1
	s_mul_hi_i32 s86, s4, 0x2e8ba2e9
	s_ashr_i32 s86, s86, 7
	s_mul_i32 s87, s86, 0x2c0
	s_sub_i32 s87, s4, s87
	s_mul_i32 s88, s87, 0xba3
	s_lshr_b32 s88, s88, 17
	s_mul_i32 s89, s88, 44
	s_sub_i32 s87, s87, s89
	s_mul_i32 s89, s86, 0xb00000
	s_mul_i32 s90, s88, 0xb0000
	s_add_u32 s89, s89, s90
	s_lshl_b32 s90, s87, 8
	s_add_u32 s89, s89, s90
	s_add_u32 s82, s24, s89
	s_addc_u32 s83, s25, 0
	s_sub_i32 s90, s87, 20
	s_cmp_gt_u32 s90, 15
	s_cbranch_scc1 .Lpc_nr1
	s_and_b32 s91, s87, 3
	s_lshr_b32 s90, s90, 2
	s_lshl_b32 s90, s90, 3
	s_lshr_b32 s90, 0x1d15141c, s90
	s_and_b32 s90, s90, 0xff
	s_lshl_b32 s91, s91, 1
	s_add_i32 s87, s90, s91

.Lpc_out1:
	s_add_i32 s87, s4, 0xfffffa80
	s_lshr_b32 s86, s87, 8
	s_bfe_u32 s88, s87, 0x40004
	s_and_b32 s87, s87, 15
	s_lshl_b32 s89, s86, 22
	s_lshl_b32 s90, s88, 18
	s_add_u32 s89, s89, s90
	s_lshl_b32 s90, s87, 8
	s_add_u32 s89, s89, s90
	s_add_u32 s82, s26, s89
	s_addc_u32 s83, s27, 0
	s_lshl_b32 s89, s86, 21
	s_lshl_b32 s90, s87, 17
	s_add_u32 s89, s89, s90
	s_lshl_b32 s90, s88, 7
	s_add_u32 s89, s89, s90
	s_add_u32 s84, s28, s89
	s_addc_u32 s85, s29, 0
	s_movk_i32 s81, 0x1000
	s_branch .Lpc_dec1
.Lpc_dummy:
	s_mov_b32 s82, s24
	s_mov_b32 s83, s25
	s_movk_i32 s81, 0x2c00
	s_mov_b32 s3, 0
	s_branch .Lpc_ldl

.Lpc_ldl:
	s_waitcnt vmcnt(0)
	s_barrier
	ds_write2_b32 v25, v208, v209 offset1:1
	ds_write2_b32 v25, v210, v211 offset0:2 offset1:3
	ds_write2_b32 v26, v212, v213 offset1:1
	ds_write2_b32 v27, v214, v215 offset1:1
	ds_write2_b32 v28, v216, v217 offset1:1
	ds_write2_b32 v29, v218, v219 offset1:1
	ds_write2_b32 v30, v220, v221 offset1:1
	ds_write2_b32 v31, v222, v223 offset1:1
	s_waitcnt lgkmcnt(0)
	s_barrier
	ds_read2_b32 v[4:5], v24 offset1:65
	ds_read2_b32 v[6:7], v24 offset0:130 offset1:195
	ds_read2_b32 v[8:9], v83 offset0:4 offset1:69
	ds_read2_b32 v[10:11], v83 offset0:134 offset1:199
	ds_read2_b32 v[12:13], v84 offset0:8 offset1:73
	ds_read2_b32 v[14:15], v84 offset0:138 offset1:203
	ds_read2_b32 v[16:17], v85 offset0:12 offset1:77
	ds_read2_b32 v[18:19], v85 offset0:142 offset1:207
	s_waitcnt lgkmcnt(7)
	v_cvt_pk_bf16_f32 v4, v4, v5
	s_waitcnt lgkmcnt(6)
	v_cvt_pk_bf16_f32 v5, v6, v7
	s_waitcnt lgkmcnt(5)
	v_cvt_pk_bf16_f32 v6, v8, v9
	s_waitcnt lgkmcnt(4)
	v_cvt_pk_bf16_f32 v7, v10, v11
	s_waitcnt lgkmcnt(3)
	v_cvt_pk_bf16_f32 v8, v12, v13
	s_waitcnt lgkmcnt(2)
	v_cvt_pk_bf16_f32 v9, v14, v15
	s_waitcnt lgkmcnt(1)
	v_cvt_pk_bf16_f32 v10, v16, v17
	s_waitcnt lgkmcnt(0)
	v_cvt_pk_bf16_f32 v11, v18, v19
	global_store_dwordx4 v82, v[4:7], s[78:79]
	global_store_dwordx4 v82, v[8:11], s[78:79] offset:16
	s_cmp_eq_u32 s3, 0
	s_cbranch_scc1 .Lpc_done
	s_barrier
	ds_write2_b32 v25, v224, v225 offset1:1
	ds_write2_b32 v25, v226, v227 offset0:2 offset1:3
	ds_write2_b32 v26, v228, v229 offset1:1
	ds_write2_b32 v27, v230, v231 offset1:1
	ds_write2_b32 v28, v232, v233 offset1:1
	ds_write2_b32 v29, v234, v235 offset1:1
	ds_write2_b32 v30, v236, v237 offset1:1
	ds_write2_b32 v31, v238, v239 offset1:1
	s_waitcnt lgkmcnt(0)
	s_barrier
	ds_read2_b32 v[4:5], v24 offset1:65
	ds_read2_b32 v[6:7], v24 offset0:130 offset1:195
	ds_read2_b32 v[8:9], v83 offset0:4 offset1:69
	ds_read2_b32 v[10:11], v83 offset0:134 offset1:199
	ds_read2_b32 v[12:13], v84 offset0:8 offset1:73
	ds_read2_b32 v[14:15], v84 offset0:138 offset1:203
	ds_read2_b32 v[16:17], v85 offset0:12 offset1:77
	ds_read2_b32 v[18:19], v85 offset0:142 offset1:207
	s_waitcnt lgkmcnt(7)
	v_cvt_pk_bf16_f32 v4, v4, v5
	s_waitcnt lgkmcnt(6)
	v_cvt_pk_bf16_f32 v5, v6, v7
	s_waitcnt lgkmcnt(5)
	v_cvt_pk_bf16_f32 v6, v8, v9
	s_waitcnt lgkmcnt(4)
	v_cvt_pk_bf16_f32 v7, v10, v11
	s_waitcnt lgkmcnt(3)
	v_cvt_pk_bf16_f32 v8, v12, v13
	s_waitcnt lgkmcnt(2)
	v_cvt_pk_bf16_f32 v9, v14, v15
	s_waitcnt lgkmcnt(1)
	v_cvt_pk_bf16_f32 v10, v16, v17
	s_waitcnt lgkmcnt(0)
	v_cvt_pk_bf16_f32 v11, v18, v19
	global_store_dwordx4 v82, v[4:7], s[84:85]
	global_store_dwordx4 v82, v[8:11], s[84:85] offset:16
